# phase 0 transposes: one extra load per item (one lane per source row) pulls the next item's 64 row segments into L2
# baseline (speedup 1.0000x reference)
_Z8mega_fwd4Args:
	s_mov_b32 s92, s2
	s_load_dwordx16 s[4:19], s[0:1], 0x0
	s_load_dwordx8 s[20:27], s[0:1], 0x40
	s_load_dword s30, s[0:1], 0x80
	s_load_dwordx4 s[36:39], s[0:1], 0x60
	s_load_dwordx2 s[2:3], s[0:1], 0x78
	v_and_b32_e32 v232, 0x3ff, v0
	v_cmp_gt_u32_e32 vcc, 2, v232
	s_waitcnt lgkmcnt(0)
	v_writelane_b32 v255, s8, 48
	v_writelane_b32 v255, s9, 49
	v_writelane_b32 v255, s10, 50
	v_writelane_b32 v255, s11, 51
	v_writelane_b32 v255, s14, 52
	v_writelane_b32 v255, s15, 53
	v_writelane_b32 v255, s18, 54
	v_writelane_b32 v255, s19, 55
	v_writelane_b32 v255, s22, 56
	v_writelane_b32 v255, s23, 57
	v_writelane_b32 v255, s24, 58
	v_writelane_b32 v255, s25, 59
	v_writelane_b32 v254, s2, 0
	s_nop 1
	v_writelane_b32 v254, s3, 1
	s_add_u32 s2, s0, 0x78
	s_addc_u32 s3, s1, 0
	s_and_saveexec_b64 s[28:29], vcc
	v_lshl_add_u32 v1, v232, 2, 0
	v_add_u32_e32 v1, 0x23fc0, v1
	v_mov_b32_e32 v2, 0
	ds_write_b32 v1, v2
	s_or_b64 exec, exec, s[28:29]
	s_load_dwordx2 s[0:1], s[0:1], 0x70
	v_cmp_eq_u32_e64 s[28:29], 0, v232
	s_waitcnt lgkmcnt(0)
	v_writelane_b32 v254, s0, 2
	s_nop 1
	v_writelane_b32 v254, s1, 3
	s_mov_b64 s[0:1], exec
	v_writelane_b32 v254, s28, 4
	s_nop 1
	v_writelane_b32 v254, s29, 5
	s_and_b64 s[28:29], s[0:1], s[28:29]
	s_mov_b64 exec, s[28:29]
	s_cbranch_execz .LBB0_4
	v_mov_b32_e32 v4, s16
	s_add_i32 s16, 0, 0x23f80
	v_mov_b32_e32 v2, s4
	v_mov_b32_e32 v3, s5
	v_mov_b32_e32 v5, s17
	v_mov_b32_e32 v1, s16
	s_add_i32 s16, 0, 0x23f90
	ds_write_b128 v1, v[2:5]
	v_mov_b32_e32 v2, s26
	v_mov_b32_e32 v3, s27
	v_mov_b32_e32 v4, s36
	v_mov_b32_e32 v5, s37
	v_mov_b32_e32 v1, s16
	ds_write_b128 v1, v[2:5]

.LBB0_22:
	v_readlane_b32 s99, v254, 10
	s_nop 3
	s_add_i32 s98, s90, s99
	s_cmpk_gt_u32 s98, 0x3cff
	s_cselect_b32 s98, s90, s98
	s_cmpk_ge_u32 s98, 0x1200
	s_cbranch_scc1 .Lpf6_1
	s_lshr_b32 s99, s98, 5
	s_mul_i32 s99, s99, 57
	s_lshr_b32 s99, s99, 9
	s_mul_i32 s101, s99, 288
	s_sub_u32 s98, s98, s101
	s_mul_i32 s99, s99, 589824
	s_lshl_b32 s98, s98, 5
	s_add_u32 s98, s98, s99
	v_readlane_b32 s100, v255, 48
	v_readlane_b32 s101, v255, 49
	v_mov_b32_e32 v101, 0x9000
	s_branch .Lpf6_e
.Lpf6_1:
	s_cmpk_ge_u32 s98, 0x1400
	s_cbranch_scc1 .Lpf6_2
	s_sub_u32 s98, s98, 0x1200
	s_lshr_b32 s99, s98, 5
	s_and_b32 s98, s98, 31
	s_lshl_b32 s99, s99, 16
	s_lshl_b32 s98, s98, 5
	s_add_u32 s98, s98, s99
	v_readlane_b32 s100, v255, 50
	v_readlane_b32 s101, v255, 51
	v_mov_b32_e32 v101, 0x1000
	s_branch .Lpf6_e
.Lpf6_2:
	s_cmpk_ge_u32 s98, 0x1800
	s_cbranch_scc1 .Lpf6_3
	s_sub_u32 s98, s98, 0x1400
	s_lshr_b32 s99, s98, 6
	s_and_b32 s98, s98, 63
	s_mul_i32 s99, s99, 197632
	s_lshl_b32 s98, s98, 5
	s_add_u32 s98, s98, s99
	v_readlane_b32 s100, v255, 52
	v_readlane_b32 s101, v255, 53
	v_mov_b32_e32 v101, 0x3040
	s_branch .Lpf6_e
.Lpf6_3:
	s_cmpk_ge_u32 s98, 0x1a00
	s_cbranch_scc1 .Lpf6_4
	s_sub_u32 s98, s98, 0x1800
	s_lshr_b32 s99, s98, 5
	s_and_b32 s98, s98, 31
	s_mul_i32 s99, s99, 197632
	s_lshl_b32 s98, s98, 5
	s_add_u32 s98, s98, s99
	s_addk_i32 s98, 0x800
	v_readlane_b32 s100, v255, 52
	v_readlane_b32 s101, v255, 53
	v_mov_b32_e32 v101, 0x3040
	s_branch .Lpf6_e
.Lpf6_4:
	s_cmpk_ge_u32 s98, 0x1c00
	s_cbranch_scc1 .Lpf6_5
	s_sub_u32 s98, s98, 0x1a00
	s_lshr_b32 s99, s98, 5
	s_and_b32 s98, s98, 31
	s_lshl_b32 s99, s99, 16
	s_lshl_b32 s98, s98, 5
	s_add_u32 s98, s98, s99
	v_readlane_b32 s100, v255, 54
	v_readlane_b32 s101, v255, 55
	v_mov_b32_e32 v101, 0x1000
	s_branch .Lpf6_e
.Lpf6_5:
	s_cmpk_ge_u32 s98, 0x3200
	s_cbranch_scc1 .Lpf6_6
	s_sub_u32 s98, s98, 0x1c00
	s_cmpk_ge_u32 s98, 0xb00
	s_cselect_b32 s100, 5767168, 0
	s_cselect_b32 s99, 0xb00, 0
	s_sub_u32 s98, s98, s99
	s_lshr_b32 s99, s98, 4
	s_mul_i32 s99, s99, 187
	s_lshr_b32 s99, s99, 11
	s_mul_i32 s101, s99, 176
	s_sub_u32 s98, s98, s101
	s_mul_i32 s99, s99, 360448
	s_lshl_b32 s98, s98, 5
	s_add_u32 s98, s98, s99
	s_add_u32 s98, s98, s100
	v_readlane_b32 s100, v255, 56
	v_readlane_b32 s101, v255, 57
	v_mov_b32_e32 v101, 0x5800
	s_branch .Lpf6_e
.Lpf6_6:
	s_sub_u32 s98, s98, 0x3200
	s_cmpk_ge_u32 s98, 0x580
	s_cselect_b32 s100, 2883584, 0
	s_cselect_b32 s99, 0x580, 0
	s_sub_u32 s98, s98, s99
	s_lshr_b32 s99, s98, 5
	s_and_b32 s98, s98, 31
	s_lshl_b32 s99, s99, 16
	s_lshl_b32 s98, s98, 5
	s_add_u32 s98, s98, s99
	s_add_u32 s98, s98, s100
	v_readlane_b32 s100, v255, 58
	v_readlane_b32 s101, v255, 59
	v_mov_b32_e32 v101, 0x1000
.Lpf6_e:
	s_nop 3
	s_lshl_b32 s98, s98, 2
	s_add_u32 s100, s100, s98
	s_addc_u32 s101, s101, 0
	v_mbcnt_lo_u32_b32 v100, -1, 0
	v_mbcnt_hi_u32_b32 v100, -1, v100
	s_nop 0
	v_mad_u64_u32 v[102:103], s[98:99], v100, v101, s[100:101]
	global_load_dword v104, v[102:103], off
	s_waitcnt vmcnt(17)
	s_waitcnt vmcnt(1)
	ds_write2_b32 v31, v27, v44 offset1:66
	ds_write2_b32 v31, v45, v46 offset0:132 offset1:198
	ds_write2_b32 v37, v47, v48 offset0:8 offset1:74
	ds_write2_b32 v37, v49, v50 offset0:140 offset1:206
	ds_write2_b32 v38, v51, v52 offset0:16 offset1:82
	ds_write2_b32 v38, v53, v54 offset0:148 offset1:214
	ds_write2_b32 v39, v55, v56 offset0:24 offset1:90
	ds_write2_b32 v39, v57, v58 offset0:156 offset1:222
	ds_write2_b32 v40, v59, v60 offset0:32 offset1:98
	ds_write2_b32 v40, v61, v62 offset0:164 offset1:230
	ds_write2_b32 v41, v63, v64 offset0:40 offset1:106
	ds_write2_b32 v41, v65, v66 offset0:172 offset1:238
	ds_write2_b32 v42, v67, v68 offset0:48 offset1:114
	ds_write2_b32 v42, v69, v70 offset0:180 offset1:246
	ds_write2_b32 v43, v71, v72 offset0:56 offset1:122
	ds_write2_b32 v43, v73, v74 offset0:188 offset1:254
	s_waitcnt lgkmcnt(0)
	ds_read2_b32 v[48:49], v33 offset1:8
	ds_read2_b32 v[50:51], v33 offset0:33 offset1:41
	ds_read2_b32 v[54:55], v33 offset0:66 offset1:74
	ds_read2_b32 v[56:57], v33 offset0:99 offset1:107
	ds_read2_b32 v[58:59], v33 offset0:132 offset1:140
	ds_read2_b32 v[60:61], v33 offset0:165 offset1:173
	ds_read2_b32 v[62:63], v33 offset0:198 offset1:206
	ds_read2_b32 v[64:65], v33 offset0:231 offset1:239
	s_waitcnt lgkmcnt(7)
	v_mov_b32_e32 v44, v48
	s_waitcnt lgkmcnt(6)
	v_mov_b32_e32 v45, v50
	s_waitcnt lgkmcnt(5)
	v_mov_b32_e32 v46, v54
	s_waitcnt lgkmcnt(4)
	v_mov_b32_e32 v47, v56
	v_pk_mul_f32 v[44:45], v[4:5], v[44:45]
	v_pk_mul_f32 v[46:47], v[6:7], v[46:47]
	v_cvt_pk_bf16_f32 v44, v44, v45
	v_cvt_pk_bf16_f32 v45, v46, v47
	s_waitcnt lgkmcnt(3)
	v_mov_b32_e32 v46, v58
	s_waitcnt lgkmcnt(2)
	v_mov_b32_e32 v47, v60
	s_waitcnt lgkmcnt(1)
	v_mov_b32_e32 v66, v62
	s_waitcnt lgkmcnt(0)
	v_mov_b32_e32 v67, v64
	v_pk_mul_f32 v[46:47], v[0:1], v[46:47]
	v_pk_mul_f32 v[66:67], v[2:3], v[66:67]
	v_cvt_pk_bf16_f32 v46, v46, v47
	v_cvt_pk_bf16_f32 v47, v66, v67
	v_add_u32_e32 v66, s16, v32
	v_ashrrev_i32_e32 v67, 31, v66
	v_lshl_add_u64 v[52:53], s[26:27], 1, v[20:21]
	v_lshlrev_b64 v[68:69], 11, v[66:67]
	v_lshl_add_u64 v[68:69], v[52:53], 0, v[68:69]
	v_mov_b32_e32 v50, v49
	v_mov_b32_e32 v56, v55
	global_store_dwordx4 v[68:69], v[44:47], off
	v_mov_b32_e32 v60, v59
	v_mov_b32_e32 v64, v63
	v_pk_mul_f32 v[44:45], v[4:5], v[50:51]
	v_pk_mul_f32 v[46:47], v[6:7], v[56:57]
	v_cvt_pk_bf16_f32 v44, v44, v45
	v_cvt_pk_bf16_f32 v45, v46, v47
	v_pk_mul_f32 v[46:47], v[0:1], v[60:61]
	v_pk_mul_f32 v[48:49], v[2:3], v[64:65]
	v_cvt_pk_bf16_f32 v46, v46, v47
	v_cvt_pk_bf16_f32 v47, v48, v49
	v_add_u32_e32 v48, 8, v66
	v_ashrrev_i32_e32 v49, 31, v48
	v_lshlrev_b64 v[48:49], 11, v[48:49]
	v_lshl_add_u64 v[48:49], v[52:53], 0, v[48:49]
	ds_read2_b32 v[50:51], v33 offset0:16 offset1:24
	ds_read2_b32 v[54:55], v33 offset0:49 offset1:57
	global_store_dwordx4 v[48:49], v[44:47], off
	ds_read2_b32 v[48:49], v33 offset0:82 offset1:90
	ds_read2_b32 v[56:57], v33 offset0:115 offset1:123
	ds_read2_b32 v[58:59], v33 offset0:148 offset1:156
	ds_read2_b32 v[60:61], v33 offset0:181 offset1:189
	ds_read2_b32 v[62:63], v33 offset0:214 offset1:222
	ds_read2_b32 v[64:65], v33 offset0:247 offset1:255
	s_waitcnt lgkmcnt(7)
	v_mov_b32_e32 v44, v50
	s_waitcnt lgkmcnt(6)
	v_mov_b32_e32 v45, v54
	s_waitcnt lgkmcnt(5)
	v_mov_b32_e32 v46, v48
	s_waitcnt lgkmcnt(4)
	v_mov_b32_e32 v47, v56
	v_pk_mul_f32 v[44:45], v[4:5], v[44:45]
	v_pk_mul_f32 v[46:47], v[6:7], v[46:47]
	v_cvt_pk_bf16_f32 v44, v44, v45
	v_cvt_pk_bf16_f32 v45, v46, v47
	s_waitcnt lgkmcnt(3)
	v_mov_b32_e32 v46, v58
	s_waitcnt lgkmcnt(2)
	v_mov_b32_e32 v47, v60
	v_mov_b32_e32 v54, v51
	v_mov_b32_e32 v56, v49
	v_mov_b32_e32 v60, v59
	v_pk_mul_f32 v[46:47], v[0:1], v[46:47]
	s_waitcnt lgkmcnt(1)
	v_mov_b32_e32 v68, v62
	s_waitcnt lgkmcnt(0)
	v_mov_b32_e32 v69, v64
	v_pk_mul_f32 v[4:5], v[4:5], v[54:55]
	v_pk_mul_f32 v[6:7], v[6:7], v[56:57]
	v_pk_mul_f32 v[0:1], v[0:1], v[60:61]
	v_mov_b32_e32 v64, v63
	v_pk_mul_f32 v[68:69], v[2:3], v[68:69]
	v_cvt_pk_bf16_f32 v4, v4, v5
	v_cvt_pk_bf16_f32 v5, v6, v7
	v_cvt_pk_bf16_f32 v6, v0, v1
	v_pk_mul_f32 v[0:1], v[2:3], v[64:65]
	v_cvt_pk_bf16_f32 v46, v46, v47
	v_cvt_pk_bf16_f32 v47, v68, v69
	v_add_u32_e32 v68, 16, v66
	v_cvt_pk_bf16_f32 v7, v0, v1
	v_add_u32_e32 v0, 24, v66
	v_ashrrev_i32_e32 v69, 31, v68
	v_ashrrev_i32_e32 v1, 31, v0
	v_lshlrev_b64 v[68:69], 11, v[68:69]
	v_lshlrev_b64 v[0:1], 11, v[0:1]
	v_lshl_add_u64 v[68:69], v[52:53], 0, v[68:69]
	v_lshl_add_u64 v[0:1], v[52:53], 0, v[0:1]
	global_store_dwordx4 v[68:69], v[44:47], off
	global_store_dwordx4 v[0:1], v[4:7], off
	s_waitcnt lgkmcnt(0)
	v_readlane_b32 s72, v254, 10

.LBB0_24:
	s_cmpk_gt_i32 s90, 0x11ff
	s_mov_b64 s[16:17], -1
	s_cbranch_scc0 .LBB0_59
	s_cmpk_gt_u32 s90, 0x13ff
	s_cbranch_scc0 .LBB0_56
	s_cmpk_gt_u32 s90, 0x17ff
	s_cbranch_scc0 .LBB0_50
	s_cmpk_gt_u32 s90, 0x19ff
	s_cbranch_scc0 .LBB0_44
	s_cmpk_gt_u32 s90, 0x1bff
	s_cbranch_scc0 .LBB0_41
	s_cmpk_gt_u32 s90, 0x31ff
	s_cbranch_scc0 .LBB0_31
	s_add_i32 s6, s90, 0xffffce00
	s_add_i32 s16, s90, 0xffffc880
	s_cmpk_lt_u32 s6, 0x580
	s_cselect_b32 s16, s6, s16
	s_cmpk_gt_u32 s6, 0x57f
	s_cselect_b32 s6, 0xb00000, 0
	s_cselect_b32 s26, 0x580000, 0
	s_add_u32 s72, s24, s6
	s_addc_u32 s73, s25, 0
	s_lshl_b32 s6, s16, 1
	s_and_b32 s17, s6, 0xfc0
	s_lshl_b32 s6, s16, 5
	s_and_b32 s16, s6, 0x3e0
	v_or_b32_e32 v0, s17, v30
	s_add_u32 s26, s34, s26
	v_lshlrev_b32_e32 v0, 12, v0
	v_mov_b32_e32 v1, v9
	s_addc_u32 s27, s35, 0
	v_lshl_add_u64 v[0:1], s[72:73], 0, v[0:1]
	s_lshl_b32 s6, s16, 2
	v_lshl_add_u64 v[0:1], v[0:1], 0, s[6:7]
	v_lshl_add_u64 v[0:1], v[0:1], 0, v[8:9]
	s_movk_i32 s6, 0x2000
	v_add_co_u32_e32 v2, vcc, s6, v0
	s_movk_i32 s6, 0x4000
	s_nop 0
	v_addc_co_u32_e32 v3, vcc, 0, v1, vcc
	v_add_co_u32_e32 v4, vcc, s6, v0
	s_movk_i32 s6, 0x6000
	s_nop 0
	v_addc_co_u32_e32 v5, vcc, 0, v1, vcc
	v_add_co_u32_e32 v6, vcc, s6, v0
	s_mov_b32 s6, 0x8000
	s_nop 0
	v_addc_co_u32_e32 v7, vcc, 0, v1, vcc
	v_add_co_u32_e32 v44, vcc, s6, v0
	s_mov_b32 s6, 0xa000
	s_nop 0
	v_addc_co_u32_e32 v45, vcc, 0, v1, vcc
	v_add_co_u32_e32 v46, vcc, s6, v0
	s_mov_b32 s6, 0xc000
	s_nop 0
	v_addc_co_u32_e32 v47, vcc, 0, v1, vcc
	v_add_co_u32_e32 v48, vcc, s6, v0
	s_mov_b32 s6, 0xe000
	s_nop 0
	v_addc_co_u32_e32 v49, vcc, 0, v1, vcc
	v_add_co_u32_e32 v50, vcc, s6, v0
	s_mov_b32 s6, 0x10000
	s_nop 0
	v_addc_co_u32_e32 v51, vcc, 0, v1, vcc
	global_load_dword v27, v[0:1], off nt
	global_load_dword v54, v[2:3], off nt
	global_load_dword v55, v[4:5], off nt
	global_load_dword v56, v[6:7], off nt
	global_load_dword v57, v[44:45], off nt
	global_load_dword v58, v[46:47], off nt
	global_load_dword v59, v[48:49], off nt
	global_load_dword v60, v[50:51], off nt
	v_add_co_u32_e32 v2, vcc, s6, v0
	s_mov_b32 s6, 0x14000
	s_nop 0
	v_addc_co_u32_e32 v3, vcc, 0, v1, vcc
	v_add_co_u32_e32 v4, vcc, s42, v0
	v_readlane_b32 s72, v254, 10
	s_nop 0
	v_addc_co_u32_e32 v5, vcc, 0, v1, vcc
	v_add_co_u32_e32 v6, vcc, s6, v0
	s_mov_b32 s6, 0x18000
	s_nop 0
	v_addc_co_u32_e32 v7, vcc, 0, v1, vcc
	v_add_co_u32_e32 v44, vcc, s43, v0
	s_nop 1
	v_addc_co_u32_e32 v45, vcc, 0, v1, vcc
	v_add_co_u32_e32 v46, vcc, s6, v0
	s_mov_b32 s6, 0x1a000
	s_nop 0
	v_addc_co_u32_e32 v47, vcc, 0, v1, vcc
	v_add_co_u32_e32 v48, vcc, s6, v0
	s_mov_b32 s6, 0x1c000
	s_nop 0
	v_addc_co_u32_e32 v49, vcc, 0, v1, vcc
	v_add_co_u32_e32 v50, vcc, s6, v0
	s_mov_b32 s6, 0x1e000
	s_nop 0
	v_addc_co_u32_e32 v51, vcc, 0, v1, vcc
	v_add_co_u32_e32 v52, vcc, s6, v0
	s_mov_b32 s6, 0x20000
	s_nop 0
	v_addc_co_u32_e32 v53, vcc, 0, v1, vcc
	global_load_dword v61, v[2:3], off nt
	global_load_dword v62, v[4:5], off nt
	global_load_dword v63, v[6:7], off nt
	global_load_dword v64, v[44:45], off nt
	global_load_dword v65, v[46:47], off nt
	global_load_dword v66, v[48:49], off nt
	global_load_dword v67, v[50:51], off nt
	global_load_dword v68, v[52:53], off nt
	v_add_co_u32_e32 v2, vcc, s6, v0
	s_mov_b32 s6, 0x22000
	s_nop 0
	v_addc_co_u32_e32 v3, vcc, 0, v1, vcc
	v_add_co_u32_e32 v4, vcc, s6, v0
	s_mov_b32 s6, 0x26000
	s_nop 0
	v_addc_co_u32_e32 v5, vcc, 0, v1, vcc
	v_add_co_u32_e32 v6, vcc, s44, v0
	s_nop 1
	v_addc_co_u32_e32 v7, vcc, 0, v1, vcc
	v_add_co_u32_e32 v44, vcc, s6, v0
	s_mov_b32 s6, 0x28000
	s_nop 0
	v_addc_co_u32_e32 v45, vcc, 0, v1, vcc
	v_add_co_u32_e32 v46, vcc, s6, v0
	s_mov_b32 s6, 0x2a000
	s_nop 0
	v_addc_co_u32_e32 v47, vcc, 0, v1, vcc
	v_add_co_u32_e32 v48, vcc, s6, v0
	s_mov_b32 s6, 0x2e000
	s_nop 0
	v_addc_co_u32_e32 v49, vcc, 0, v1, vcc
	v_add_co_u32_e32 v50, vcc, s45, v0
	s_nop 1
	v_addc_co_u32_e32 v51, vcc, 0, v1, vcc
	v_add_co_u32_e32 v52, vcc, s6, v0
	s_mov_b32 s6, 0x30000
	s_nop 0
	v_addc_co_u32_e32 v53, vcc, 0, v1, vcc
	global_load_dword v69, v[2:3], off nt
	global_load_dword v70, v[4:5], off nt
	global_load_dword v71, v[6:7], off nt
	global_load_dword v72, v[44:45], off nt
	global_load_dword v73, v[46:47], off nt
	global_load_dword v74, v[48:49], off nt
	global_load_dword v75, v[50:51], off nt
	s_nop 0
	global_load_dword v52, v[52:53], off nt
	v_add_co_u32_e32 v2, vcc, s6, v0
	s_mov_b32 s6, 0x32000
	s_nop 0
	v_addc_co_u32_e32 v3, vcc, 0, v1, vcc
	v_add_co_u32_e32 v4, vcc, s6, v0
	s_mov_b32 s6, 0x34000
	s_nop 0
	v_addc_co_u32_e32 v5, vcc, 0, v1, vcc
	v_add_co_u32_e32 v6, vcc, s6, v0
	s_mov_b32 s6, 0x38000
	s_nop 0
	v_addc_co_u32_e32 v7, vcc, 0, v1, vcc
	v_add_co_u32_e32 v44, vcc, s46, v0
	s_nop 1
	v_addc_co_u32_e32 v45, vcc, 0, v1, vcc
	v_add_co_u32_e32 v46, vcc, s6, v0
	s_mov_b32 s6, 0x3a000
	s_nop 0
	v_addc_co_u32_e32 v47, vcc, 0, v1, vcc
	v_add_co_u32_e32 v48, vcc, s6, v0
	s_mov_b32 s6, 0x3c000
	s_nop 0
	v_addc_co_u32_e32 v49, vcc, 0, v1, vcc
	v_add_co_u32_e32 v50, vcc, s6, v0
	s_mov_b32 s6, 0x3e000
	s_nop 0
	v_addc_co_u32_e32 v51, vcc, 0, v1, vcc
	v_add_co_u32_e32 v0, vcc, s6, v0
	s_lshl_b32 s6, s17, 1
	s_nop 0
	v_addc_co_u32_e32 v1, vcc, 0, v1, vcc
	global_load_dword v2, v[2:3], off nt
	s_nop 0
	global_load_dword v3, v[4:5], off nt
	s_nop 0
	global_load_dword v4, v[6:7], off nt
	global_load_dword v5, v[44:45], off nt
	s_nop 0
	global_load_dword v6, v[46:47], off nt
	global_load_dword v7, v[48:49], off nt
	global_load_dword v44, v[50:51], off nt
	s_nop 0
	global_load_dword v0, v[0:1], off nt
	v_readlane_b32 s99, v254, 10
	s_nop 3
	s_add_i32 s98, s90, s99
	s_cmpk_gt_u32 s98, 0x3cff
	s_cselect_b32 s98, s90, s98
	s_cmpk_ge_u32 s98, 0x1200
	s_cbranch_scc1 .Lpf5_1
	s_lshr_b32 s99, s98, 5
	s_mul_i32 s99, s99, 57
	s_lshr_b32 s99, s99, 9
	s_mul_i32 s101, s99, 288
	s_sub_u32 s98, s98, s101
	s_mul_i32 s99, s99, 589824
	s_lshl_b32 s98, s98, 5
	s_add_u32 s98, s98, s99
	v_readlane_b32 s100, v255, 48
	v_readlane_b32 s101, v255, 49
	v_mov_b32_e32 v101, 0x9000
	s_branch .Lpf5_e

.Lpf5_e:
	s_nop 3
	s_lshl_b32 s98, s98, 2
	s_add_u32 s100, s100, s98
	s_addc_u32 s101, s101, 0
	v_mbcnt_lo_u32_b32 v100, -1, 0
	v_mbcnt_hi_u32_b32 v100, -1, v100
	s_nop 0
	v_mad_u64_u32 v[102:103], s[98:99], v100, v101, s[100:101]
	global_load_dword v104, v[102:103], off
	s_waitcnt vmcnt(17)
	s_waitcnt vmcnt(1)
	ds_write2_b32 v31, v27, v54 offset1:66
	ds_write2_b32 v31, v55, v56 offset0:132 offset1:198
	ds_write2_b32 v37, v57, v58 offset0:8 offset1:74
	ds_write2_b32 v37, v59, v60 offset0:140 offset1:206
	ds_write2_b32 v38, v61, v62 offset0:16 offset1:82
	ds_write2_b32 v38, v63, v64 offset0:148 offset1:214
	ds_write2_b32 v39, v65, v66 offset0:24 offset1:90
	ds_write2_b32 v39, v67, v68 offset0:156 offset1:222
	ds_write2_b32 v40, v69, v70 offset0:32 offset1:98
	ds_write2_b32 v40, v71, v72 offset0:164 offset1:230
	ds_write2_b32 v41, v73, v74 offset0:40 offset1:106
	ds_write2_b32 v41, v75, v52 offset0:172 offset1:238
	ds_write2_b32 v42, v2, v3 offset0:48 offset1:114
	ds_write2_b32 v42, v4, v5 offset0:180 offset1:246
	ds_write2_b32 v43, v6, v7 offset0:56 offset1:122
	ds_write2_b32 v43, v44, v0 offset0:188 offset1:254
	s_waitcnt lgkmcnt(0)
	ds_read2_b32 v[4:5], v33 offset0:33 offset1:41
	ds_read2_b32 v[6:7], v33 offset1:8
	ds_read2_b32 v[44:45], v33 offset0:66 offset1:74
	ds_read2_b32 v[46:47], v33 offset0:99 offset1:107
	ds_read2_b32 v[48:49], v33 offset0:132 offset1:140
	ds_read2_b32 v[50:51], v33 offset0:165 offset1:173
	ds_read2_b32 v[52:53], v33 offset0:198 offset1:206
	ds_read2_b32 v[54:55], v33 offset0:231 offset1:239
	s_add_u32 s26, s26, s6
	s_waitcnt lgkmcnt(6)
	v_cvt_pk_bf16_f32 v0, v6, v4
	v_or_b32_e32 v4, s16, v32
	s_addc_u32 s27, s27, 0
	v_mov_b32_e32 v27, v9
	v_mul_u32_u24_e32 v4, 0xb00, v4
	v_lshl_add_u64 v[56:57], s[26:27], 0, v[26:27]
	v_lshlrev_b32_e32 v58, 1, v4
	v_mov_b32_e32 v59, v9
	s_waitcnt lgkmcnt(4)
	v_cvt_pk_bf16_f32 v1, v44, v46
	s_waitcnt lgkmcnt(2)
	v_cvt_pk_bf16_f32 v2, v48, v50
	s_waitcnt lgkmcnt(0)
	v_cvt_pk_bf16_f32 v3, v52, v54
	v_lshl_add_u64 v[58:59], v[56:57], 0, v[58:59]
	v_or_b32_e32 v4, s16, v34
	global_store_dwordx4 v[58:59], v[0:3], off
	v_mul_u32_u24_e32 v4, 0xb00, v4
	v_lshlrev_b32_e32 v4, 1, v4
	v_cvt_pk_bf16_f32 v0, v7, v5
	v_cvt_pk_bf16_f32 v1, v45, v47
	v_cvt_pk_bf16_f32 v2, v49, v51
	v_cvt_pk_bf16_f32 v3, v53, v55
	v_mov_b32_e32 v5, v9
	ds_read2_b32 v[6:7], v33 offset0:16 offset1:24
	ds_read2_b32 v[44:45], v33 offset0:49 offset1:57
	ds_read2_b32 v[46:47], v33 offset0:82 offset1:90
	ds_read2_b32 v[48:49], v33 offset0:115 offset1:123
	ds_read2_b32 v[50:51], v33 offset0:148 offset1:156
	ds_read2_b32 v[52:53], v33 offset0:181 offset1:189
	ds_read2_b32 v[54:55], v33 offset0:214 offset1:222
	ds_read2_b32 v[58:59], v33 offset0:247 offset1:255
	v_lshl_add_u64 v[4:5], v[56:57], 0, v[4:5]
	global_store_dwordx4 v[4:5], v[0:3], off
	v_or_b32_e32 v4, s16, v35
	v_mul_u32_u24_e32 v4, 0xb00, v4
	v_lshlrev_b32_e32 v4, 1, v4
	v_mov_b32_e32 v5, v9
	s_waitcnt lgkmcnt(6)
	v_cvt_pk_bf16_f32 v0, v6, v44
	s_waitcnt lgkmcnt(4)
	v_cvt_pk_bf16_f32 v1, v46, v48
	s_waitcnt lgkmcnt(2)
	v_cvt_pk_bf16_f32 v2, v50, v52
	s_waitcnt lgkmcnt(0)
	v_cvt_pk_bf16_f32 v3, v54, v58
	v_lshl_add_u64 v[4:5], v[56:57], 0, v[4:5]
	global_store_dwordx4 v[4:5], v[0:3], off
	v_or_b32_e32 v4, s16, v36
	v_mul_u32_u24_e32 v4, 0xb00, v4
	v_lshlrev_b32_e32 v4, 1, v4
	v_mov_b32_e32 v5, v9
	v_cvt_pk_bf16_f32 v0, v7, v45
	v_cvt_pk_bf16_f32 v1, v47, v49
	v_cvt_pk_bf16_f32 v2, v51, v53
	v_cvt_pk_bf16_f32 v3, v55, v59
	v_lshl_add_u64 v[4:5], v[56:57], 0, v[4:5]
	global_store_dwordx4 v[4:5], v[0:3], off
	s_waitcnt lgkmcnt(0)
	s_mov_b64 s[16:17], 0

.Lpf4_e:
	s_nop 3
	s_lshl_b32 s98, s98, 2
	s_add_u32 s100, s100, s98
	s_addc_u32 s101, s101, 0
	v_mbcnt_lo_u32_b32 v100, -1, 0
	v_mbcnt_hi_u32_b32 v100, -1, v100
	s_nop 0
	v_mad_u64_u32 v[102:103], s[98:99], v100, v101, s[100:101]
	global_load_dword v104, v[102:103], off
	s_waitcnt vmcnt(17)
	s_waitcnt vmcnt(1)
	ds_write2_b32 v31, v27, v44 offset1:66
	ds_write2_b32 v31, v45, v46 offset0:132 offset1:198
	ds_write2_b32 v37, v47, v48 offset0:8 offset1:74
	ds_write2_b32 v37, v49, v50 offset0:140 offset1:206
	ds_write2_b32 v38, v51, v52 offset0:16 offset1:82
	ds_write2_b32 v38, v53, v54 offset0:148 offset1:214
	ds_write2_b32 v39, v55, v56 offset0:24 offset1:90
	ds_write2_b32 v39, v57, v58 offset0:156 offset1:222
	ds_write2_b32 v40, v59, v60 offset0:32 offset1:98
	ds_write2_b32 v40, v61, v62 offset0:164 offset1:230
	ds_write2_b32 v41, v63, v64 offset0:40 offset1:106
	ds_write2_b32 v41, v65, v66 offset0:172 offset1:238
	ds_write2_b32 v42, v67, v68 offset0:48 offset1:114
	ds_write2_b32 v42, v69, v70 offset0:180 offset1:246
	ds_write2_b32 v43, v71, v72 offset0:56 offset1:122
	ds_write2_b32 v43, v73, v74 offset0:188 offset1:254
	s_waitcnt lgkmcnt(0)
	ds_read2_b32 v[48:49], v33 offset1:8
	ds_read2_b32 v[50:51], v33 offset0:33 offset1:41
	ds_read2_b32 v[54:55], v33 offset0:66 offset1:74
	ds_read2_b32 v[56:57], v33 offset0:99 offset1:107
	ds_read2_b32 v[58:59], v33 offset0:132 offset1:140
	ds_read2_b32 v[60:61], v33 offset0:165 offset1:173
	ds_read2_b32 v[62:63], v33 offset0:198 offset1:206
	ds_read2_b32 v[64:65], v33 offset0:231 offset1:239
	s_and_b64 s[16:17], s[16:17], exec
	s_cselect_b32 s16, 0xb00000, 0
	s_waitcnt lgkmcnt(7)
	v_mov_b32_e32 v44, v48
	s_waitcnt lgkmcnt(6)
	v_mov_b32_e32 v45, v50
	s_waitcnt lgkmcnt(5)
	v_mov_b32_e32 v46, v54
	s_waitcnt lgkmcnt(4)
	v_mov_b32_e32 v47, v56
	s_add_u32 s16, s36, s16
	v_pk_mul_f32 v[44:45], v[4:5], v[44:45]
	v_pk_mul_f32 v[46:47], v[6:7], v[46:47]
	s_addc_u32 s17, s37, 0
	s_lshl_b32 s6, s6, 1
	v_cvt_pk_bf16_f32 v44, v44, v45
	v_cvt_pk_bf16_f32 v45, v46, v47
	s_waitcnt lgkmcnt(3)
	v_mov_b32_e32 v46, v58
	s_waitcnt lgkmcnt(2)
	v_mov_b32_e32 v47, v60
	s_waitcnt lgkmcnt(1)
	v_mov_b32_e32 v66, v62
	s_waitcnt lgkmcnt(0)
	v_mov_b32_e32 v67, v64
	s_add_u32 s16, s16, s6
	v_pk_mul_f32 v[46:47], v[0:1], v[46:47]
	v_pk_mul_f32 v[66:67], v[2:3], v[66:67]
	s_addc_u32 s17, s17, 0
	v_mov_b32_e32 v27, v9
	v_cvt_pk_bf16_f32 v46, v46, v47
	v_cvt_pk_bf16_f32 v47, v66, v67
	v_add_u32_e32 v66, s72, v32
	v_mov_b32_e32 v67, v9
	v_lshl_add_u64 v[52:53], s[16:17], 0, v[26:27]
	v_lshlrev_b64 v[66:67], 11, v[66:67]
	v_lshl_add_u64 v[66:67], v[52:53], 0, v[66:67]
	v_mov_b32_e32 v50, v49
	v_mov_b32_e32 v56, v55
	global_store_dwordx4 v[66:67], v[44:47], off
	v_mov_b32_e32 v60, v59
	v_mov_b32_e32 v64, v63
	v_pk_mul_f32 v[44:45], v[4:5], v[50:51]
	v_pk_mul_f32 v[46:47], v[6:7], v[56:57]
	v_cvt_pk_bf16_f32 v44, v44, v45
	v_cvt_pk_bf16_f32 v45, v46, v47
	v_pk_mul_f32 v[46:47], v[0:1], v[60:61]
	v_pk_mul_f32 v[48:49], v[2:3], v[64:65]
	v_cvt_pk_bf16_f32 v46, v46, v47
	v_cvt_pk_bf16_f32 v47, v48, v49
	v_add_u32_e32 v48, s72, v34
	v_mov_b32_e32 v49, v9
	v_lshlrev_b64 v[48:49], 11, v[48:49]
	v_lshl_add_u64 v[48:49], v[52:53], 0, v[48:49]
	ds_read2_b32 v[50:51], v33 offset0:16 offset1:24
	ds_read2_b32 v[54:55], v33 offset0:49 offset1:57
	global_store_dwordx4 v[48:49], v[44:47], off
	ds_read2_b32 v[48:49], v33 offset0:82 offset1:90
	ds_read2_b32 v[56:57], v33 offset0:115 offset1:123
	ds_read2_b32 v[58:59], v33 offset0:148 offset1:156
	ds_read2_b32 v[60:61], v33 offset0:181 offset1:189
	ds_read2_b32 v[62:63], v33 offset0:214 offset1:222
	ds_read2_b32 v[64:65], v33 offset0:247 offset1:255
	s_waitcnt lgkmcnt(7)
	v_mov_b32_e32 v44, v50
	s_waitcnt lgkmcnt(6)
	v_mov_b32_e32 v45, v54
	s_waitcnt lgkmcnt(5)
	v_mov_b32_e32 v46, v48
	s_waitcnt lgkmcnt(4)
	v_mov_b32_e32 v47, v56
	v_pk_mul_f32 v[44:45], v[4:5], v[44:45]
	v_pk_mul_f32 v[46:47], v[6:7], v[46:47]
	v_cvt_pk_bf16_f32 v44, v44, v45
	v_cvt_pk_bf16_f32 v45, v46, v47
	s_waitcnt lgkmcnt(3)
	v_mov_b32_e32 v46, v58
	s_waitcnt lgkmcnt(2)
	v_mov_b32_e32 v47, v60
	v_mov_b32_e32 v54, v51
	v_mov_b32_e32 v56, v49
	v_mov_b32_e32 v60, v59
	v_pk_mul_f32 v[46:47], v[0:1], v[46:47]
	s_waitcnt lgkmcnt(1)
	v_mov_b32_e32 v66, v62
	s_waitcnt lgkmcnt(0)
	v_mov_b32_e32 v67, v64
	v_pk_mul_f32 v[4:5], v[4:5], v[54:55]
	v_pk_mul_f32 v[6:7], v[6:7], v[56:57]
	v_pk_mul_f32 v[0:1], v[0:1], v[60:61]
	v_mov_b32_e32 v64, v63
	v_pk_mul_f32 v[66:67], v[2:3], v[66:67]
	v_cvt_pk_bf16_f32 v4, v4, v5
	v_cvt_pk_bf16_f32 v5, v6, v7
	v_cvt_pk_bf16_f32 v6, v0, v1
	v_pk_mul_f32 v[0:1], v[2:3], v[64:65]
	v_cvt_pk_bf16_f32 v46, v46, v47
	v_cvt_pk_bf16_f32 v47, v66, v67
	v_add_u32_e32 v66, s72, v35
	v_mov_b32_e32 v67, v9
	v_cvt_pk_bf16_f32 v7, v0, v1
	v_add_u32_e32 v0, s72, v36
	v_mov_b32_e32 v1, v9
	v_lshlrev_b64 v[66:67], 11, v[66:67]
	v_lshlrev_b64 v[0:1], 11, v[0:1]
	v_lshl_add_u64 v[66:67], v[52:53], 0, v[66:67]
	v_lshl_add_u64 v[0:1], v[52:53], 0, v[0:1]
	global_store_dwordx4 v[66:67], v[44:47], off
	global_store_dwordx4 v[0:1], v[4:7], off
	s_waitcnt lgkmcnt(0)
	s_mov_b32 s92, s91
	v_readlane_b32 s72, v254, 10

.LBB0_41:
	s_andn2_b64 vcc, exec, s[16:17]
	s_cbranch_vccnz .LBB0_43
	s_and_b32 s6, s40, 0x3fc0
	s_add_i32 s16, s6, 0xffffcc00
	v_or_b32_e32 v0, s16, v30
	v_mov_b32_e32 v1, v9
	s_and_b32 s26, s38, 0x3e0
	v_lshlrev_b64 v[0:1], 12, v[0:1]
	v_lshl_add_u64 v[0:1], s[18:19], 0, v[0:1]
	s_lshl_b32 s6, s26, 2
	v_lshl_add_u64 v[0:1], v[0:1], 0, s[6:7]
	v_lshl_add_u64 v[0:1], v[0:1], 0, v[8:9]
	v_add_co_u32_e32 v2, vcc, 0x2000, v0
	s_mov_b32 s17, s7
	s_nop 0
	v_addc_co_u32_e32 v3, vcc, 0, v1, vcc
	v_add_co_u32_e32 v4, vcc, 0x4000, v0
	s_nop 1
	v_addc_co_u32_e32 v5, vcc, 0, v1, vcc
	v_add_co_u32_e32 v6, vcc, 0x6000, v0
	s_nop 1
	v_addc_co_u32_e32 v7, vcc, 0, v1, vcc
	v_add_co_u32_e32 v44, vcc, 0x8000, v0
	s_nop 1
	v_addc_co_u32_e32 v45, vcc, 0, v1, vcc
	v_add_co_u32_e32 v46, vcc, 0xa000, v0
	s_nop 1
	v_addc_co_u32_e32 v47, vcc, 0, v1, vcc
	v_add_co_u32_e32 v48, vcc, 0xc000, v0
	s_nop 1
	v_addc_co_u32_e32 v49, vcc, 0, v1, vcc
	v_add_co_u32_e32 v50, vcc, 0xe000, v0
	s_nop 1
	v_addc_co_u32_e32 v51, vcc, 0, v1, vcc
	global_load_dword v27, v[0:1], off nt
	global_load_dword v54, v[2:3], off nt
	global_load_dword v55, v[4:5], off nt
	global_load_dword v56, v[6:7], off nt
	global_load_dword v57, v[44:45], off nt
	global_load_dword v58, v[46:47], off nt
	global_load_dword v59, v[48:49], off nt
	global_load_dword v60, v[50:51], off nt
	v_add_co_u32_e32 v2, vcc, 0x10000, v0
	s_nop 1
	v_addc_co_u32_e32 v3, vcc, 0, v1, vcc
	v_add_co_u32_e32 v4, vcc, 0x12000, v0
	s_nop 1
	v_addc_co_u32_e32 v5, vcc, 0, v1, vcc
	v_add_co_u32_e32 v6, vcc, 0x14000, v0
	s_nop 1
	v_addc_co_u32_e32 v7, vcc, 0, v1, vcc
	v_add_co_u32_e32 v44, vcc, 0x16000, v0
	s_nop 1
	v_addc_co_u32_e32 v45, vcc, 0, v1, vcc
	v_add_co_u32_e32 v46, vcc, 0x18000, v0
	s_nop 1
	v_addc_co_u32_e32 v47, vcc, 0, v1, vcc
	v_add_co_u32_e32 v48, vcc, 0x1a000, v0
	s_nop 1
	v_addc_co_u32_e32 v49, vcc, 0, v1, vcc
	v_add_co_u32_e32 v50, vcc, 0x1c000, v0
	s_nop 1
	v_addc_co_u32_e32 v51, vcc, 0, v1, vcc
	v_add_co_u32_e32 v52, vcc, 0x1e000, v0
	s_nop 1
	v_addc_co_u32_e32 v53, vcc, 0, v1, vcc
	global_load_dword v61, v[2:3], off nt
	global_load_dword v62, v[4:5], off nt
	global_load_dword v63, v[6:7], off nt
	global_load_dword v64, v[44:45], off nt
	global_load_dword v65, v[46:47], off nt
	global_load_dword v66, v[48:49], off nt
	global_load_dword v67, v[50:51], off nt
	global_load_dword v68, v[52:53], off nt
	v_add_co_u32_e32 v2, vcc, 0x20000, v0
	s_nop 1
	v_addc_co_u32_e32 v3, vcc, 0, v1, vcc
	v_add_co_u32_e32 v4, vcc, 0x22000, v0
	s_nop 1
	v_addc_co_u32_e32 v5, vcc, 0, v1, vcc
	v_add_co_u32_e32 v6, vcc, 0x24000, v0
	s_nop 1
	v_addc_co_u32_e32 v7, vcc, 0, v1, vcc
	v_add_co_u32_e32 v44, vcc, 0x26000, v0
	s_nop 1
	v_addc_co_u32_e32 v45, vcc, 0, v1, vcc
	v_add_co_u32_e32 v46, vcc, 0x28000, v0
	s_nop 1
	v_addc_co_u32_e32 v47, vcc, 0, v1, vcc
	v_add_co_u32_e32 v48, vcc, 0x2a000, v0
	s_nop 1
	v_addc_co_u32_e32 v49, vcc, 0, v1, vcc
	v_add_co_u32_e32 v50, vcc, 0x2c000, v0
	s_nop 1
	v_addc_co_u32_e32 v51, vcc, 0, v1, vcc
	v_add_co_u32_e32 v52, vcc, 0x2e000, v0
	s_nop 1
	v_addc_co_u32_e32 v53, vcc, 0, v1, vcc
	global_load_dword v69, v[2:3], off nt
	global_load_dword v70, v[4:5], off nt
	global_load_dword v71, v[6:7], off nt
	global_load_dword v72, v[44:45], off nt
	global_load_dword v73, v[46:47], off nt
	global_load_dword v74, v[48:49], off nt
	global_load_dword v75, v[50:51], off nt
	s_nop 0
	global_load_dword v52, v[52:53], off nt
	v_add_co_u32_e32 v2, vcc, 0x30000, v0
	s_nop 1
	v_addc_co_u32_e32 v3, vcc, 0, v1, vcc
	v_add_co_u32_e32 v4, vcc, 0x32000, v0
	s_nop 1
	v_addc_co_u32_e32 v5, vcc, 0, v1, vcc
	v_add_co_u32_e32 v6, vcc, 0x34000, v0
	s_nop 1
	v_addc_co_u32_e32 v7, vcc, 0, v1, vcc
	v_add_co_u32_e32 v44, vcc, 0x36000, v0
	s_nop 1
	v_addc_co_u32_e32 v45, vcc, 0, v1, vcc
	v_add_co_u32_e32 v46, vcc, 0x38000, v0
	s_nop 1
	v_addc_co_u32_e32 v47, vcc, 0, v1, vcc
	v_add_co_u32_e32 v48, vcc, 0x3a000, v0
	s_nop 1
	v_addc_co_u32_e32 v49, vcc, 0, v1, vcc
	v_add_co_u32_e32 v50, vcc, 0x3c000, v0
	s_nop 1
	v_addc_co_u32_e32 v51, vcc, 0, v1, vcc
	v_add_co_u32_e32 v0, vcc, 0x3e000, v0
	s_nop 1
	v_addc_co_u32_e32 v1, vcc, 0, v1, vcc
	global_load_dword v2, v[2:3], off nt
	s_nop 0
	global_load_dword v3, v[4:5], off nt
	s_nop 0
	global_load_dword v4, v[6:7], off nt
	global_load_dword v5, v[44:45], off nt
	s_nop 0
	global_load_dword v6, v[46:47], off nt
	global_load_dword v7, v[48:49], off nt
	global_load_dword v44, v[50:51], off nt
	s_nop 0
	global_load_dword v0, v[0:1], off nt
	v_readlane_b32 s99, v254, 10
	s_nop 3
	s_add_i32 s98, s90, s99
	s_cmpk_gt_u32 s98, 0x3cff
	s_cselect_b32 s98, s90, s98
	s_cmpk_ge_u32 s98, 0x1200
	s_cbranch_scc1 .Lpf3_1
	s_lshr_b32 s99, s98, 5
	s_mul_i32 s99, s99, 57
	s_lshr_b32 s99, s99, 9
	s_mul_i32 s101, s99, 288
	s_sub_u32 s98, s98, s101
	s_mul_i32 s99, s99, 589824
	s_lshl_b32 s98, s98, 5
	s_add_u32 s98, s98, s99
	v_readlane_b32 s100, v255, 48
	v_readlane_b32 s101, v255, 49
	v_mov_b32_e32 v101, 0x9000
	s_branch .Lpf3_e

.Lpf3_e:
	s_nop 3
	s_lshl_b32 s98, s98, 2
	s_add_u32 s100, s100, s98
	s_addc_u32 s101, s101, 0
	v_mbcnt_lo_u32_b32 v100, -1, 0
	v_mbcnt_hi_u32_b32 v100, -1, v100
	s_nop 0
	v_mad_u64_u32 v[102:103], s[98:99], v100, v101, s[100:101]
	global_load_dword v104, v[102:103], off
	s_waitcnt vmcnt(17)
	s_waitcnt vmcnt(1)
	ds_write2_b32 v31, v27, v54 offset1:66
	ds_write2_b32 v31, v55, v56 offset0:132 offset1:198
	ds_write2_b32 v37, v57, v58 offset0:8 offset1:74
	ds_write2_b32 v37, v59, v60 offset0:140 offset1:206
	ds_write2_b32 v38, v61, v62 offset0:16 offset1:82
	ds_write2_b32 v38, v63, v64 offset0:148 offset1:214
	ds_write2_b32 v39, v65, v66 offset0:24 offset1:90
	ds_write2_b32 v39, v67, v68 offset0:156 offset1:222
	ds_write2_b32 v40, v69, v70 offset0:32 offset1:98
	ds_write2_b32 v40, v71, v72 offset0:164 offset1:230
	ds_write2_b32 v41, v73, v74 offset0:40 offset1:106
	ds_write2_b32 v41, v75, v52 offset0:172 offset1:238
	ds_write2_b32 v42, v2, v3 offset0:48 offset1:114
	ds_write2_b32 v42, v4, v5 offset0:180 offset1:246
	ds_write2_b32 v43, v6, v7 offset0:56 offset1:122
	ds_write2_b32 v43, v44, v0 offset0:188 offset1:254
	s_waitcnt lgkmcnt(0)
	ds_read2_b32 v[4:5], v33 offset0:33 offset1:41
	ds_read2_b32 v[6:7], v33 offset1:8
	ds_read2_b32 v[44:45], v33 offset0:66 offset1:74
	ds_read2_b32 v[46:47], v33 offset0:99 offset1:107
	ds_read2_b32 v[48:49], v33 offset0:132 offset1:140
	ds_read2_b32 v[50:51], v33 offset0:165 offset1:173
	ds_read2_b32 v[52:53], v33 offset0:198 offset1:206
	ds_read2_b32 v[54:55], v33 offset0:231 offset1:239
	s_waitcnt lgkmcnt(6)
	v_cvt_pk_bf16_f32 v0, v6, v4
	v_or_b32_e32 v4, s26, v32
	v_lshl_add_u64 v[56:57], s[16:17], 1, v[12:13]
	v_lshlrev_b32_e32 v58, 11, v4
	v_mov_b32_e32 v59, v9
	s_waitcnt lgkmcnt(4)
	v_cvt_pk_bf16_f32 v1, v44, v46
	s_waitcnt lgkmcnt(2)
	v_cvt_pk_bf16_f32 v2, v48, v50
	s_waitcnt lgkmcnt(0)
	v_cvt_pk_bf16_f32 v3, v52, v54
	v_lshl_add_u64 v[58:59], v[56:57], 0, v[58:59]
	global_store_dwordx4 v[58:59], v[0:3], off
	v_or_b32_e32 v4, s26, v34
	v_lshlrev_b32_e32 v4, 11, v4
	v_cvt_pk_bf16_f32 v0, v7, v5
	v_cvt_pk_bf16_f32 v1, v45, v47
	v_cvt_pk_bf16_f32 v2, v49, v51
	v_cvt_pk_bf16_f32 v3, v53, v55
	ds_read2_b32 v[6:7], v33 offset0:49 offset1:57
	ds_read2_b32 v[44:45], v33 offset0:16 offset1:24
	ds_read2_b32 v[46:47], v33 offset0:82 offset1:90
	ds_read2_b32 v[48:49], v33 offset0:115 offset1:123
	ds_read2_b32 v[50:51], v33 offset0:148 offset1:156
	ds_read2_b32 v[52:53], v33 offset0:181 offset1:189
	ds_read2_b32 v[54:55], v33 offset0:214 offset1:222
	ds_read2_b32 v[58:59], v33 offset0:247 offset1:255
	v_mov_b32_e32 v5, v9
	v_lshl_add_u64 v[4:5], v[56:57], 0, v[4:5]
	global_store_dwordx4 v[4:5], v[0:3], off
	v_or_b32_e32 v4, s26, v35
	v_lshlrev_b32_e32 v4, 11, v4
	v_mov_b32_e32 v5, v9
	s_waitcnt lgkmcnt(6)
	v_cvt_pk_bf16_f32 v0, v44, v6
	s_waitcnt lgkmcnt(4)
	v_cvt_pk_bf16_f32 v1, v46, v48
	s_waitcnt lgkmcnt(2)
	v_cvt_pk_bf16_f32 v2, v50, v52
	s_waitcnt lgkmcnt(0)
	v_cvt_pk_bf16_f32 v3, v54, v58
	v_lshl_add_u64 v[4:5], v[56:57], 0, v[4:5]
	global_store_dwordx4 v[4:5], v[0:3], off
	v_or_b32_e32 v4, s26, v36
	v_lshlrev_b32_e32 v4, 11, v4
	v_mov_b32_e32 v5, v9
	v_cvt_pk_bf16_f32 v0, v45, v7
	v_cvt_pk_bf16_f32 v1, v47, v49
	v_cvt_pk_bf16_f32 v2, v51, v53
	v_cvt_pk_bf16_f32 v3, v55, v59
	v_lshl_add_u64 v[4:5], v[56:57], 0, v[4:5]
	global_store_dwordx4 v[4:5], v[0:3], off
	s_waitcnt lgkmcnt(0)

.Lpf2_e:
	s_nop 3
	s_lshl_b32 s98, s98, 2
	s_add_u32 s100, s100, s98
	s_addc_u32 s101, s101, 0
	v_mbcnt_lo_u32_b32 v100, -1, 0
	v_mbcnt_hi_u32_b32 v100, -1, v100
	s_nop 0
	v_mad_u64_u32 v[102:103], s[98:99], v100, v101, s[100:101]
	global_load_dword v104, v[102:103], off
	s_waitcnt vmcnt(17)
	s_waitcnt vmcnt(1)
	ds_write2_b32 v31, v27, v44 offset1:66
	ds_write2_b32 v31, v45, v46 offset0:132 offset1:198
	ds_write2_b32 v37, v47, v48 offset0:8 offset1:74
	ds_write2_b32 v37, v49, v50 offset0:140 offset1:206
	ds_write2_b32 v38, v51, v52 offset0:16 offset1:82
	ds_write2_b32 v38, v53, v54 offset0:148 offset1:214
	ds_write2_b32 v39, v55, v56 offset0:24 offset1:90
	ds_write2_b32 v39, v57, v58 offset0:156 offset1:222
	ds_write2_b32 v40, v59, v60 offset0:32 offset1:98
	ds_write2_b32 v40, v61, v62 offset0:164 offset1:230
	ds_write2_b32 v41, v63, v64 offset0:40 offset1:106
	ds_write2_b32 v41, v65, v66 offset0:172 offset1:238
	ds_write2_b32 v42, v67, v68 offset0:48 offset1:114
	ds_write2_b32 v42, v69, v70 offset0:180 offset1:246
	ds_write2_b32 v43, v71, v72 offset0:56 offset1:122
	ds_write2_b32 v43, v73, v74 offset0:188 offset1:254
	s_waitcnt lgkmcnt(0)
	ds_read2_b32 v[48:49], v33 offset1:8
	ds_read2_b32 v[50:51], v33 offset0:33 offset1:41
	ds_read2_b32 v[54:55], v33 offset0:66 offset1:74
	ds_read2_b32 v[56:57], v33 offset0:99 offset1:107
	ds_read2_b32 v[58:59], v33 offset0:132 offset1:140
	ds_read2_b32 v[60:61], v33 offset0:165 offset1:173
	ds_read2_b32 v[62:63], v33 offset0:198 offset1:206
	ds_read2_b32 v[64:65], v33 offset0:231 offset1:239
	s_waitcnt lgkmcnt(7)
	v_mov_b32_e32 v44, v48
	s_waitcnt lgkmcnt(6)
	v_mov_b32_e32 v45, v50
	s_waitcnt lgkmcnt(5)
	v_mov_b32_e32 v46, v54
	s_waitcnt lgkmcnt(4)
	v_mov_b32_e32 v47, v56
	v_pk_mul_f32 v[44:45], v[4:5], v[44:45]
	v_pk_mul_f32 v[46:47], v[6:7], v[46:47]
	v_cvt_pk_bf16_f32 v44, v44, v45
	v_cvt_pk_bf16_f32 v45, v46, v47
	s_waitcnt lgkmcnt(3)
	v_mov_b32_e32 v46, v58
	s_waitcnt lgkmcnt(2)
	v_mov_b32_e32 v47, v60
	s_waitcnt lgkmcnt(1)
	v_mov_b32_e32 v66, v62
	s_waitcnt lgkmcnt(0)
	v_mov_b32_e32 v67, v64
	v_pk_mul_f32 v[46:47], v[0:1], v[46:47]
	v_pk_mul_f32 v[66:67], v[2:3], v[66:67]
	v_or_b32_e32 v27, s16, v32
	v_lshl_add_u64 v[52:53], s[6:7], 1, v[16:17]
	v_cvt_pk_bf16_f32 v46, v46, v47
	v_cvt_pk_bf16_f32 v47, v66, v67
	v_lshlrev_b32_e32 v66, 11, v27
	v_mov_b32_e32 v67, v9
	v_lshl_add_u64 v[66:67], v[52:53], 0, v[66:67]
	v_mov_b32_e32 v50, v49
	v_mov_b32_e32 v56, v55
	global_store_dwordx4 v[66:67], v[44:47], off
	v_mov_b32_e32 v60, v59
	v_mov_b32_e32 v64, v63
	v_pk_mul_f32 v[44:45], v[4:5], v[50:51]
	v_pk_mul_f32 v[46:47], v[6:7], v[56:57]
	v_cvt_pk_bf16_f32 v44, v44, v45
	v_cvt_pk_bf16_f32 v45, v46, v47
	v_pk_mul_f32 v[46:47], v[0:1], v[60:61]
	v_pk_mul_f32 v[48:49], v[2:3], v[64:65]
	v_or_b32_e32 v27, s16, v34
	v_cvt_pk_bf16_f32 v46, v46, v47
	v_cvt_pk_bf16_f32 v47, v48, v49
	v_lshlrev_b32_e32 v48, 11, v27
	v_mov_b32_e32 v49, v9
	v_lshl_add_u64 v[48:49], v[52:53], 0, v[48:49]
	ds_read2_b32 v[50:51], v33 offset0:16 offset1:24
	ds_read2_b32 v[54:55], v33 offset0:49 offset1:57
	global_store_dwordx4 v[48:49], v[44:47], off
	ds_read2_b32 v[48:49], v33 offset0:82 offset1:90
	ds_read2_b32 v[56:57], v33 offset0:115 offset1:123
	ds_read2_b32 v[58:59], v33 offset0:148 offset1:156
	ds_read2_b32 v[60:61], v33 offset0:181 offset1:189
	ds_read2_b32 v[62:63], v33 offset0:214 offset1:222
	ds_read2_b32 v[64:65], v33 offset0:247 offset1:255
	s_waitcnt lgkmcnt(7)
	v_mov_b32_e32 v44, v50
	s_waitcnt lgkmcnt(6)
	v_mov_b32_e32 v45, v54
	s_waitcnt lgkmcnt(5)
	v_mov_b32_e32 v46, v48
	s_waitcnt lgkmcnt(4)
	v_mov_b32_e32 v47, v56
	v_pk_mul_f32 v[44:45], v[4:5], v[44:45]
	v_pk_mul_f32 v[46:47], v[6:7], v[46:47]
	v_cvt_pk_bf16_f32 v44, v44, v45
	v_cvt_pk_bf16_f32 v45, v46, v47
	s_waitcnt lgkmcnt(3)
	v_mov_b32_e32 v46, v58
	s_waitcnt lgkmcnt(2)
	v_mov_b32_e32 v47, v60
	v_mov_b32_e32 v54, v51
	v_mov_b32_e32 v56, v49
	v_mov_b32_e32 v60, v59
	v_pk_mul_f32 v[46:47], v[0:1], v[46:47]
	s_waitcnt lgkmcnt(0)
	v_mov_b32_e32 v67, v64
	v_pk_mul_f32 v[4:5], v[4:5], v[54:55]
	v_pk_mul_f32 v[6:7], v[6:7], v[56:57]
	v_pk_mul_f32 v[0:1], v[0:1], v[60:61]
	v_mov_b32_e32 v64, v63
	v_mov_b32_e32 v66, v62
	v_cvt_pk_bf16_f32 v4, v4, v5
	v_cvt_pk_bf16_f32 v5, v6, v7
	v_cvt_pk_bf16_f32 v6, v0, v1
	v_pk_mul_f32 v[0:1], v[2:3], v[64:65]
	v_pk_mul_f32 v[66:67], v[2:3], v[66:67]
	v_or_b32_e32 v27, s16, v35
	v_cvt_pk_bf16_f32 v7, v0, v1
	v_or_b32_e32 v0, s16, v36
	v_cvt_pk_bf16_f32 v46, v46, v47
	v_cvt_pk_bf16_f32 v47, v66, v67
	v_lshlrev_b32_e32 v66, 11, v27
	v_mov_b32_e32 v67, v9
	v_lshlrev_b32_e32 v0, 11, v0
	v_mov_b32_e32 v1, v9
	v_lshl_add_u64 v[66:67], v[52:53], 0, v[66:67]
	v_lshl_add_u64 v[0:1], v[52:53], 0, v[0:1]
	global_store_dwordx4 v[66:67], v[44:47], off
	global_store_dwordx4 v[0:1], v[4:7], off
	s_waitcnt lgkmcnt(0)

.Lpf1_e:
	s_nop 3
	s_lshl_b32 s98, s98, 2
	s_add_u32 s100, s100, s98
	s_addc_u32 s101, s101, 0
	v_mbcnt_lo_u32_b32 v100, -1, 0
	v_mbcnt_hi_u32_b32 v100, -1, v100
	s_nop 0
	v_mad_u64_u32 v[102:103], s[98:99], v100, v101, s[100:101]
	global_load_dword v104, v[102:103], off
	s_waitcnt vmcnt(17)
	s_waitcnt vmcnt(1)
	ds_write2_b32 v31, v27, v44 offset1:66
	ds_write2_b32 v31, v45, v46 offset0:132 offset1:198
	ds_write2_b32 v37, v47, v48 offset0:8 offset1:74
	ds_write2_b32 v37, v49, v50 offset0:140 offset1:206
	ds_write2_b32 v38, v51, v52 offset0:16 offset1:82
	ds_write2_b32 v38, v53, v54 offset0:148 offset1:214
	ds_write2_b32 v39, v55, v56 offset0:24 offset1:90
	ds_write2_b32 v39, v57, v58 offset0:156 offset1:222
	ds_write2_b32 v40, v59, v60 offset0:32 offset1:98
	ds_write2_b32 v40, v61, v62 offset0:164 offset1:230
	ds_write2_b32 v41, v63, v64 offset0:40 offset1:106
	ds_write2_b32 v41, v65, v66 offset0:172 offset1:238
	ds_write2_b32 v42, v67, v68 offset0:48 offset1:114
	ds_write2_b32 v42, v69, v70 offset0:180 offset1:246
	ds_write2_b32 v43, v71, v72 offset0:56 offset1:122
	ds_write2_b32 v43, v73, v74 offset0:188 offset1:254
	s_waitcnt lgkmcnt(0)
	ds_read2_b32 v[48:49], v33 offset1:8
	ds_read2_b32 v[50:51], v33 offset0:33 offset1:41
	ds_read2_b32 v[54:55], v33 offset0:66 offset1:74
	ds_read2_b32 v[56:57], v33 offset0:99 offset1:107
	ds_read2_b32 v[58:59], v33 offset0:132 offset1:140
	ds_read2_b32 v[60:61], v33 offset0:165 offset1:173
	ds_read2_b32 v[62:63], v33 offset0:198 offset1:206
	ds_read2_b32 v[64:65], v33 offset0:231 offset1:239
	s_waitcnt lgkmcnt(7)
	v_mov_b32_e32 v44, v48
	s_waitcnt lgkmcnt(6)
	v_mov_b32_e32 v45, v50
	s_waitcnt lgkmcnt(5)
	v_mov_b32_e32 v46, v54
	s_waitcnt lgkmcnt(4)
	v_mov_b32_e32 v47, v56
	v_pk_mul_f32 v[44:45], v[4:5], v[44:45]
	v_pk_mul_f32 v[46:47], v[6:7], v[46:47]
	v_cvt_pk_bf16_f32 v44, v44, v45
	v_cvt_pk_bf16_f32 v45, v46, v47
	s_waitcnt lgkmcnt(3)
	v_mov_b32_e32 v46, v58
	s_waitcnt lgkmcnt(2)
	v_mov_b32_e32 v47, v60
	s_waitcnt lgkmcnt(1)
	v_mov_b32_e32 v66, v62
	s_waitcnt lgkmcnt(0)
	v_mov_b32_e32 v67, v64
	v_pk_mul_f32 v[46:47], v[0:1], v[46:47]
	v_pk_mul_f32 v[66:67], v[2:3], v[66:67]
	v_or_b32_e32 v27, s16, v32
	v_lshl_add_u64 v[52:53], s[6:7], 1, v[18:19]
	v_cvt_pk_bf16_f32 v46, v46, v47
	v_cvt_pk_bf16_f32 v47, v66, v67
	v_lshlrev_b32_e32 v66, 11, v27
	v_mov_b32_e32 v67, v9
	v_lshl_add_u64 v[66:67], v[52:53], 0, v[66:67]
	v_mov_b32_e32 v50, v49
	v_mov_b32_e32 v56, v55
	global_store_dwordx4 v[66:67], v[44:47], off
	v_mov_b32_e32 v60, v59
	v_mov_b32_e32 v64, v63
	v_pk_mul_f32 v[44:45], v[4:5], v[50:51]
	v_pk_mul_f32 v[46:47], v[6:7], v[56:57]
	v_cvt_pk_bf16_f32 v44, v44, v45
	v_cvt_pk_bf16_f32 v45, v46, v47
	v_pk_mul_f32 v[46:47], v[0:1], v[60:61]
	v_pk_mul_f32 v[48:49], v[2:3], v[64:65]
	v_or_b32_e32 v27, s16, v34
	v_cvt_pk_bf16_f32 v46, v46, v47
	v_cvt_pk_bf16_f32 v47, v48, v49
	v_lshlrev_b32_e32 v48, 11, v27
	v_mov_b32_e32 v49, v9
	v_lshl_add_u64 v[48:49], v[52:53], 0, v[48:49]
	ds_read2_b32 v[50:51], v33 offset0:16 offset1:24
	ds_read2_b32 v[54:55], v33 offset0:49 offset1:57
	global_store_dwordx4 v[48:49], v[44:47], off
	ds_read2_b32 v[48:49], v33 offset0:82 offset1:90
	ds_read2_b32 v[56:57], v33 offset0:115 offset1:123
	ds_read2_b32 v[58:59], v33 offset0:148 offset1:156
	ds_read2_b32 v[60:61], v33 offset0:181 offset1:189
	ds_read2_b32 v[62:63], v33 offset0:214 offset1:222
	ds_read2_b32 v[64:65], v33 offset0:247 offset1:255
	s_waitcnt lgkmcnt(7)
	v_mov_b32_e32 v44, v50
	s_waitcnt lgkmcnt(6)
	v_mov_b32_e32 v45, v54
	s_waitcnt lgkmcnt(5)
	v_mov_b32_e32 v46, v48
	s_waitcnt lgkmcnt(4)
	v_mov_b32_e32 v47, v56
	v_pk_mul_f32 v[44:45], v[4:5], v[44:45]
	v_pk_mul_f32 v[46:47], v[6:7], v[46:47]
	v_cvt_pk_bf16_f32 v44, v44, v45
	v_cvt_pk_bf16_f32 v45, v46, v47
	s_waitcnt lgkmcnt(3)
	v_mov_b32_e32 v46, v58
	s_waitcnt lgkmcnt(2)
	v_mov_b32_e32 v47, v60
	v_mov_b32_e32 v54, v51
	v_mov_b32_e32 v56, v49
	v_mov_b32_e32 v60, v59
	v_pk_mul_f32 v[46:47], v[0:1], v[46:47]
	s_waitcnt lgkmcnt(0)
	v_mov_b32_e32 v67, v64
	v_pk_mul_f32 v[4:5], v[4:5], v[54:55]
	v_pk_mul_f32 v[6:7], v[6:7], v[56:57]
	v_pk_mul_f32 v[0:1], v[0:1], v[60:61]
	v_mov_b32_e32 v64, v63
	v_mov_b32_e32 v66, v62
	v_cvt_pk_bf16_f32 v4, v4, v5
	v_cvt_pk_bf16_f32 v5, v6, v7
	v_cvt_pk_bf16_f32 v6, v0, v1
	v_pk_mul_f32 v[0:1], v[2:3], v[64:65]
	v_pk_mul_f32 v[66:67], v[2:3], v[66:67]
	v_or_b32_e32 v27, s16, v35
	v_cvt_pk_bf16_f32 v7, v0, v1
	v_or_b32_e32 v0, s16, v36
	v_cvt_pk_bf16_f32 v46, v46, v47
	v_cvt_pk_bf16_f32 v47, v66, v67
	v_lshlrev_b32_e32 v66, 11, v27
	v_mov_b32_e32 v67, v9
	v_lshlrev_b32_e32 v0, 11, v0
	v_mov_b32_e32 v1, v9
	v_lshl_add_u64 v[66:67], v[52:53], 0, v[66:67]
	v_lshl_add_u64 v[0:1], v[52:53], 0, v[0:1]
	global_store_dwordx4 v[66:67], v[44:47], off
	global_store_dwordx4 v[0:1], v[4:7], off
	s_waitcnt lgkmcnt(0)

.LBB0_56:
	s_andn2_b64 vcc, exec, s[16:17]
	s_cbranch_vccnz .LBB0_58
	s_and_b32 s6, s40, 0x3fc0
	s_add_i32 s16, s6, 0xffffdc00
	v_or_b32_e32 v0, s16, v30
	v_mov_b32_e32 v1, v9
	s_and_b32 s26, s38, 0x3e0
	v_lshlrev_b64 v[0:1], 12, v[0:1]
	v_lshl_add_u64 v[0:1], s[10:11], 0, v[0:1]
	s_lshl_b32 s6, s26, 2
	v_lshl_add_u64 v[0:1], v[0:1], 0, s[6:7]
	v_lshl_add_u64 v[0:1], v[0:1], 0, v[8:9]
	v_add_co_u32_e32 v2, vcc, 0x2000, v0
	s_mov_b32 s17, s7
	s_nop 0
	v_addc_co_u32_e32 v3, vcc, 0, v1, vcc
	v_add_co_u32_e32 v4, vcc, 0x4000, v0
	s_nop 1
	v_addc_co_u32_e32 v5, vcc, 0, v1, vcc
	v_add_co_u32_e32 v6, vcc, 0x6000, v0
	s_nop 1
	v_addc_co_u32_e32 v7, vcc, 0, v1, vcc
	v_add_co_u32_e32 v44, vcc, 0x8000, v0
	s_nop 1
	v_addc_co_u32_e32 v45, vcc, 0, v1, vcc
	v_add_co_u32_e32 v46, vcc, 0xa000, v0
	s_nop 1
	v_addc_co_u32_e32 v47, vcc, 0, v1, vcc
	v_add_co_u32_e32 v48, vcc, 0xc000, v0
	s_nop 1
	v_addc_co_u32_e32 v49, vcc, 0, v1, vcc
	v_add_co_u32_e32 v50, vcc, 0xe000, v0
	s_nop 1
	v_addc_co_u32_e32 v51, vcc, 0, v1, vcc
	global_load_dword v27, v[0:1], off nt
	global_load_dword v54, v[2:3], off nt
	global_load_dword v55, v[4:5], off nt
	global_load_dword v56, v[6:7], off nt
	global_load_dword v57, v[44:45], off nt
	global_load_dword v58, v[46:47], off nt
	global_load_dword v59, v[48:49], off nt
	global_load_dword v60, v[50:51], off nt
	v_add_co_u32_e32 v2, vcc, 0x10000, v0
	s_nop 1
	v_addc_co_u32_e32 v3, vcc, 0, v1, vcc
	v_add_co_u32_e32 v4, vcc, 0x12000, v0
	s_nop 1
	v_addc_co_u32_e32 v5, vcc, 0, v1, vcc
	v_add_co_u32_e32 v6, vcc, 0x14000, v0
	s_nop 1
	v_addc_co_u32_e32 v7, vcc, 0, v1, vcc
	v_add_co_u32_e32 v44, vcc, 0x16000, v0
	s_nop 1
	v_addc_co_u32_e32 v45, vcc, 0, v1, vcc
	v_add_co_u32_e32 v46, vcc, 0x18000, v0
	s_nop 1
	v_addc_co_u32_e32 v47, vcc, 0, v1, vcc
	v_add_co_u32_e32 v48, vcc, 0x1a000, v0
	s_nop 1
	v_addc_co_u32_e32 v49, vcc, 0, v1, vcc
	v_add_co_u32_e32 v50, vcc, 0x1c000, v0
	s_nop 1
	v_addc_co_u32_e32 v51, vcc, 0, v1, vcc
	v_add_co_u32_e32 v52, vcc, 0x1e000, v0
	s_nop 1
	v_addc_co_u32_e32 v53, vcc, 0, v1, vcc
	global_load_dword v61, v[2:3], off nt
	global_load_dword v62, v[4:5], off nt
	global_load_dword v63, v[6:7], off nt
	global_load_dword v64, v[44:45], off nt
	global_load_dword v65, v[46:47], off nt
	global_load_dword v66, v[48:49], off nt
	global_load_dword v67, v[50:51], off nt
	global_load_dword v68, v[52:53], off nt
	v_add_co_u32_e32 v2, vcc, 0x20000, v0
	s_nop 1
	v_addc_co_u32_e32 v3, vcc, 0, v1, vcc
	v_add_co_u32_e32 v4, vcc, 0x22000, v0
	s_nop 1
	v_addc_co_u32_e32 v5, vcc, 0, v1, vcc
	v_add_co_u32_e32 v6, vcc, 0x24000, v0
	s_nop 1
	v_addc_co_u32_e32 v7, vcc, 0, v1, vcc
	v_add_co_u32_e32 v44, vcc, 0x26000, v0
	s_nop 1
	v_addc_co_u32_e32 v45, vcc, 0, v1, vcc
	v_add_co_u32_e32 v46, vcc, 0x28000, v0
	s_nop 1
	v_addc_co_u32_e32 v47, vcc, 0, v1, vcc
	v_add_co_u32_e32 v48, vcc, 0x2a000, v0
	s_nop 1
	v_addc_co_u32_e32 v49, vcc, 0, v1, vcc
	v_add_co_u32_e32 v50, vcc, 0x2c000, v0
	s_nop 1
	v_addc_co_u32_e32 v51, vcc, 0, v1, vcc
	v_add_co_u32_e32 v52, vcc, 0x2e000, v0
	s_nop 1
	v_addc_co_u32_e32 v53, vcc, 0, v1, vcc
	global_load_dword v69, v[2:3], off nt
	global_load_dword v70, v[4:5], off nt
	global_load_dword v71, v[6:7], off nt
	global_load_dword v72, v[44:45], off nt
	global_load_dword v73, v[46:47], off nt
	global_load_dword v74, v[48:49], off nt
	global_load_dword v75, v[50:51], off nt
	s_nop 0
	global_load_dword v52, v[52:53], off nt
	v_add_co_u32_e32 v2, vcc, 0x30000, v0
	s_nop 1
	v_addc_co_u32_e32 v3, vcc, 0, v1, vcc
	v_add_co_u32_e32 v4, vcc, 0x32000, v0
	s_nop 1
	v_addc_co_u32_e32 v5, vcc, 0, v1, vcc
	v_add_co_u32_e32 v6, vcc, 0x34000, v0
	s_nop 1
	v_addc_co_u32_e32 v7, vcc, 0, v1, vcc
	v_add_co_u32_e32 v44, vcc, 0x36000, v0
	s_nop 1
	v_addc_co_u32_e32 v45, vcc, 0, v1, vcc
	v_add_co_u32_e32 v46, vcc, 0x38000, v0
	s_nop 1
	v_addc_co_u32_e32 v47, vcc, 0, v1, vcc
	v_add_co_u32_e32 v48, vcc, 0x3a000, v0
	s_nop 1
	v_addc_co_u32_e32 v49, vcc, 0, v1, vcc
	v_add_co_u32_e32 v50, vcc, 0x3c000, v0
	s_nop 1
	v_addc_co_u32_e32 v51, vcc, 0, v1, vcc
	v_add_co_u32_e32 v0, vcc, 0x3e000, v0
	s_nop 1
	v_addc_co_u32_e32 v1, vcc, 0, v1, vcc
	global_load_dword v2, v[2:3], off nt
	s_nop 0
	global_load_dword v3, v[4:5], off nt
	s_nop 0
	global_load_dword v4, v[6:7], off nt
	global_load_dword v5, v[44:45], off nt
	s_nop 0
	global_load_dword v6, v[46:47], off nt
	global_load_dword v7, v[48:49], off nt
	global_load_dword v44, v[50:51], off nt
	s_nop 0
	global_load_dword v0, v[0:1], off nt
	v_readlane_b32 s99, v254, 10
	s_nop 3
	s_add_i32 s98, s90, s99
	s_cmpk_gt_u32 s98, 0x3cff
	s_cselect_b32 s98, s90, s98
	s_cmpk_ge_u32 s98, 0x1200
	s_cbranch_scc1 .Lpf0_1
	s_lshr_b32 s99, s98, 5
	s_mul_i32 s99, s99, 57
	s_lshr_b32 s99, s99, 9
	s_mul_i32 s101, s99, 288
	s_sub_u32 s98, s98, s101
	s_mul_i32 s99, s99, 589824
	s_lshl_b32 s98, s98, 5
	s_add_u32 s98, s98, s99
	v_readlane_b32 s100, v255, 48
	v_readlane_b32 s101, v255, 49
	v_mov_b32_e32 v101, 0x9000
	s_branch .Lpf0_e

.Lpf0_e:
	s_nop 3
	s_lshl_b32 s98, s98, 2
	s_add_u32 s100, s100, s98
	s_addc_u32 s101, s101, 0
	v_mbcnt_lo_u32_b32 v100, -1, 0
	v_mbcnt_hi_u32_b32 v100, -1, v100
	s_nop 0
	v_mad_u64_u32 v[102:103], s[98:99], v100, v101, s[100:101]
	global_load_dword v104, v[102:103], off
	s_waitcnt vmcnt(17)
	s_waitcnt vmcnt(1)
	ds_write2_b32 v31, v27, v54 offset1:66
	ds_write2_b32 v31, v55, v56 offset0:132 offset1:198
	ds_write2_b32 v37, v57, v58 offset0:8 offset1:74
	ds_write2_b32 v37, v59, v60 offset0:140 offset1:206
	ds_write2_b32 v38, v61, v62 offset0:16 offset1:82
	ds_write2_b32 v38, v63, v64 offset0:148 offset1:214
	ds_write2_b32 v39, v65, v66 offset0:24 offset1:90
	ds_write2_b32 v39, v67, v68 offset0:156 offset1:222
	ds_write2_b32 v40, v69, v70 offset0:32 offset1:98
	ds_write2_b32 v40, v71, v72 offset0:164 offset1:230
	ds_write2_b32 v41, v73, v74 offset0:40 offset1:106
	ds_write2_b32 v41, v75, v52 offset0:172 offset1:238
	ds_write2_b32 v42, v2, v3 offset0:48 offset1:114
	ds_write2_b32 v42, v4, v5 offset0:180 offset1:246
	ds_write2_b32 v43, v6, v7 offset0:56 offset1:122
	ds_write2_b32 v43, v44, v0 offset0:188 offset1:254
	s_waitcnt lgkmcnt(0)
	ds_read2_b32 v[4:5], v33 offset0:33 offset1:41
	ds_read2_b32 v[6:7], v33 offset1:8
	ds_read2_b32 v[44:45], v33 offset0:66 offset1:74
	ds_read2_b32 v[46:47], v33 offset0:99 offset1:107
	ds_read2_b32 v[48:49], v33 offset0:132 offset1:140
	ds_read2_b32 v[50:51], v33 offset0:165 offset1:173
	ds_read2_b32 v[52:53], v33 offset0:198 offset1:206
	ds_read2_b32 v[54:55], v33 offset0:231 offset1:239
	s_waitcnt lgkmcnt(6)
	v_cvt_pk_bf16_f32 v0, v6, v4
	v_or_b32_e32 v4, s26, v32
	v_lshl_add_u64 v[56:57], s[16:17], 1, v[14:15]
	v_lshlrev_b32_e32 v58, 11, v4
	v_mov_b32_e32 v59, v9
	s_waitcnt lgkmcnt(4)
	v_cvt_pk_bf16_f32 v1, v44, v46
	s_waitcnt lgkmcnt(2)
	v_cvt_pk_bf16_f32 v2, v48, v50
	s_waitcnt lgkmcnt(0)
	v_cvt_pk_bf16_f32 v3, v52, v54
	v_lshl_add_u64 v[58:59], v[56:57], 0, v[58:59]
	global_store_dwordx4 v[58:59], v[0:3], off
	v_or_b32_e32 v4, s26, v34
	v_lshlrev_b32_e32 v4, 11, v4
	v_cvt_pk_bf16_f32 v0, v7, v5
	v_cvt_pk_bf16_f32 v1, v45, v47
	v_cvt_pk_bf16_f32 v2, v49, v51
	v_cvt_pk_bf16_f32 v3, v53, v55
	ds_read2_b32 v[6:7], v33 offset0:49 offset1:57
	ds_read2_b32 v[44:45], v33 offset0:16 offset1:24
	ds_read2_b32 v[46:47], v33 offset0:82 offset1:90
	ds_read2_b32 v[48:49], v33 offset0:115 offset1:123
	ds_read2_b32 v[50:51], v33 offset0:148 offset1:156
	ds_read2_b32 v[52:53], v33 offset0:181 offset1:189
	ds_read2_b32 v[54:55], v33 offset0:214 offset1:222
	ds_read2_b32 v[58:59], v33 offset0:247 offset1:255
	v_mov_b32_e32 v5, v9
	v_lshl_add_u64 v[4:5], v[56:57], 0, v[4:5]
	global_store_dwordx4 v[4:5], v[0:3], off
	v_or_b32_e32 v4, s26, v35
	v_lshlrev_b32_e32 v4, 11, v4
	v_mov_b32_e32 v5, v9
	s_waitcnt lgkmcnt(6)
	v_cvt_pk_bf16_f32 v0, v44, v6
	s_waitcnt lgkmcnt(4)
	v_cvt_pk_bf16_f32 v1, v46, v48
	s_waitcnt lgkmcnt(2)
	v_cvt_pk_bf16_f32 v2, v50, v52
	s_waitcnt lgkmcnt(0)
	v_cvt_pk_bf16_f32 v3, v54, v58
	v_lshl_add_u64 v[4:5], v[56:57], 0, v[4:5]
	global_store_dwordx4 v[4:5], v[0:3], off
	v_or_b32_e32 v4, s26, v36
	v_lshlrev_b32_e32 v4, 11, v4
	v_mov_b32_e32 v5, v9
	v_cvt_pk_bf16_f32 v0, v45, v7
	v_cvt_pk_bf16_f32 v1, v47, v49
	v_cvt_pk_bf16_f32 v2, v51, v53
	v_cvt_pk_bf16_f32 v3, v55, v59
	v_lshl_add_u64 v[4:5], v[56:57], 0, v[4:5]
	global_store_dwordx4 v[4:5], v[0:3], off
	s_waitcnt lgkmcnt(0)
